# P0 weight conversion (w_in/wa/wb/wo of layer 0) also through the three-in-flight routine
# speedup vs baseline: 1.0126x; 1.0048x over previous
;     unsigned char* ws = a.ws;
;     int base = 0;
; #pragma unroll 1
;     for (int mi = 0; mi < 7 * DEPTH; ++mi) {
;         if (!((mask >> mi) & 1u)) continue;
;         const int l = mi / 7, kind = mi - 7 * l;
;         const float* W; const float* ks = nullptr; bf16_t* WT; int K, N, rm = 0;
;         if (kind == 0)      { W = a.in[2] + (size_t)l * 2048 * 7680;  K = 2048; N = 7680; WT = (bf16_t*)(ws + WS_WIN + l * SZ_WIN); ks = a.in[1] + l * 2048; rm = 3; }
;         else if (kind == 1) { W = a.in[10] + (size_t)l * 1024 * 2048; K = 1024; N = 2048; WT = (bf16_t*)(ws + WS_WA + l * SZ_WA); }
;         else if (kind == 2) { W = a.in[11] + (size_t)l * 1024 * 2048; K = 1024; N = 2048; WT = (bf16_t*)(ws + WS_WB + l * SZ_WB); }
;         else if (kind == 3) { W = a.in[12] + (size_t)l * 2048 * 2048; K = 2048; N = 2048; WT = (bf16_t*)(ws + WS_WO + l * SZ_WO); }
;         else if (kind == 4) { W = a.in[14] + (size_t)l * 2048 * 5632; K = 2048; N = 5632; WT = (bf16_t*)(ws + WS_WGU + l * SZ_WGU); ks = a.in[13] + l * 2048; rm = 1; }
;         else if (kind == 5) { W = a.in[15] + (size_t)l * 2048 * 5632; K = 2048; N = 5632; WT = (bf16_t*)(ws + WS_WGU + l * SZ_WGU); ks = a.in[13] + l * 2048; rm = 2; }
;         else                { W = a.in[16] + (size_t)l * 5632 * 2048; K = 5632; N = 2048; WT = (bf16_t*)(ws + WS_WD + l * SZ_WD); }
;         const int nitems = (K >> 6) * (N >> 5);
;         int ilo = 0, ihi = nitems; if ((fmask >> mi) & 1u) { ilo = (nitems * flo) >> 4; ihi = (nitems * fhi) >> 4; }
;         const int cnt = ihi - ilo;
;         int first = (gw - base) % NGW; if (first < 0) first += NGW;
;         for (int it = first; it < cnt; it += NGW) tr_item(W, K, N, WT, ks, rm, ilo + it, lane);
;         base = (base + cnt) % NGW;
; __global__ void __launch_bounds__(NTHREADS, 2) mk_fwd(Args args) {
;     ...
;     if (KON(0) && IN(0)) { const int vcu = (G % 8 == 0) ? (blk % 8) * (G / 8) + blk / 8 : blk; p0_prologue(args, vcu * NWAVES + wave, G * NWAVES, lane, 0x000Fu | 0x0010u | 0x0800u, true, 0x0810u, 0, 10); }
.LBB0_8:
	s_lshl_b32 s4, s4, 3
	s_add_i32 s12, s4, s2
	s_lshl_b32 s14, s3, 3
	s_add_u32 s15, s92, 0x5e00000
	s_addc_u32 s26, s93, 0
	s_add_u32 s27, s92, 0x4e00000
	s_addc_u32 s28, s93, 0
	s_add_u32 s29, s92, 0x4600000
	s_addc_u32 s30, s93, 0
	s_add_u32 s31, s92, 0x3e00000
	s_addc_u32 s33, s93, 0
	s_add_u32 s34, s92, 0x200000
	s_addc_u32 s35, s93, 0
	s_add_u32 s36, s92, 0xb600000
	s_addc_u32 s37, s93, 0
	s_abs_i32 s38, s14
	v_cvt_f32_u32_e32 v1, s38
	s_sub_i32 s4, 0, s38
	v_lshlrev_b32_e32 v3, 2, v204
	v_and_b32_e32 v38, 56, v204
	v_rcp_iflag_f32_e32 v2, v1
	v_and_b32_e32 v1, 7, v204
	v_and_b32_e32 v39, 28, v3
	s_lshl_b32 s9, s3, 9
	v_mul_f32_e32 v2, 0x4f7ffffe, v2
	v_cvt_u32_f32_e32 v2, v2
	s_lshl_b32 s39, s3, 8
	s_movk_i32 s41, 0xf00
	s_movk_i32 s42, 0xe00
	v_readfirstlane_b32 s5, v2
	s_mul_i32 s4, s4, s5
	s_mul_hi_u32 s4, s5, s4
	v_mov_b32_e32 v2, 0xffffe400
	s_add_i32 s40, s5, s4
	v_lshl_or_b32 v40, v1, 3, v2
	s_cmpk_lg_u32 s3, 0x100
	s_cbranch_scc1 .Lslot_p0_orig
	v_and_b32_e32 v43, 63, v204
	v_lshrrev_b32_e32 v102, 3, v43
	v_and_b32_e32 v103, 7, v43
	v_lshlrev_b32_e32 v110, 5, v102
	s_mov_b32 s46, 0
.Lsl_p0_dispatch:
	s_cmp_eq_u32 s46, 0
	s_cbranch_scc1 .Lsl_p0_set0
	s_cmp_eq_u32 s46, 1
	s_cbranch_scc1 .Lsl_p0_set1
	s_cmp_eq_u32 s46, 2
	s_cbranch_scc1 .Lsl_p0_set2
	s_cmp_eq_u32 s46, 3
	s_cbranch_scc1 .Lsl_p0_set3
	s_branch .LBB0_53
.Lsl_p0_set0:
	v_readlane_b32 s22, v250, 6
	v_readlane_b32 s23, v250, 7
	v_readlane_b32 s24, v250, 36
	v_readlane_b32 s25, v250, 37
	v_readlane_b32 s44, v250, 4
	v_readlane_b32 s45, v250, 5
	v_mul_u32_u24_e32 v104, 0x3c000, v102
	v_lshl_add_u32 v104, v103, 4, v104
	v_mul_u32_u24_e32 v105, 0x4000, v103
	v_lshl_add_u32 v105, v102, 4, v105
	s_add_u32 s24, s24, 0x1c0000
	s_addc_u32 s25, s25, 0
	s_mov_b32 s48, 0x7800
	s_mov_b32 s49, 0x1e0000
	s_movk_i32 s50, 8739
	s_mov_b32 s51, 21
	s_movk_i32 s52, 240
	s_movk_i32 s53, 0x1000
	s_mov_b32 s54, 3
	s_mov_b32 s55, 1
	s_movk_i32 s56, 0
	s_movk_i32 s47, 7680
	s_sub_i32 s4, s12, 0
	s_and_b32 s4, s4, 2047
	s_branch .Lsl_p0_loop
.Lsl_p0_set1:
	v_readlane_b32 s22, v250, 22
	v_readlane_b32 s23, v250, 23
	v_readlane_b32 s24, v250, 36
	v_readlane_b32 s25, v250, 37
	v_mul_u32_u24_e32 v104, 0x10000, v102
	v_lshl_add_u32 v104, v103, 4, v104
	v_mul_u32_u24_e32 v105, 0x2000, v103
	v_lshl_add_u32 v105, v102, 4, v105
	s_add_u32 s24, s24, 0x3dc0000
	s_addc_u32 s25, s25, 0
	s_mov_b32 s48, 0x2000
	s_mov_b32 s49, 0x80000
	s_movk_i32 s50, 1
	s_mov_b32 s51, 6
	s_movk_i32 s52, 64
	s_movk_i32 s53, 0x800
	s_mov_b32 s54, 0
	s_mov_b32 s55, 0
	s_movk_i32 s56, 0
	s_movk_i32 s47, 1024
	s_sub_i32 s4, s12, 1536
	s_and_b32 s4, s4, 2047
	s_branch .Lsl_p0_loop
.Lsl_p0_set2:
	v_readlane_b32 s22, v250, 24
	v_readlane_b32 s23, v250, 25
	v_readlane_b32 s24, v250, 36
	v_readlane_b32 s25, v250, 37
	v_mul_u32_u24_e32 v104, 0x10000, v102
	v_lshl_add_u32 v104, v103, 4, v104
	v_mul_u32_u24_e32 v105, 0x2000, v103
	v_lshl_add_u32 v105, v102, 4, v105
	s_add_u32 s24, s24, 0x45c0000
	s_addc_u32 s25, s25, 0
	s_mov_b32 s48, 0x2000
	s_mov_b32 s49, 0x80000
	s_movk_i32 s50, 1
	s_mov_b32 s51, 6
	s_movk_i32 s52, 64
	s_movk_i32 s53, 0x800
	s_mov_b32 s54, 0
	s_mov_b32 s55, 0
	s_movk_i32 s56, 0
	s_movk_i32 s47, 1024
	s_sub_i32 s4, s12, 512
	s_and_b32 s4, s4, 2047
	s_branch .Lsl_p0_loop
.Lsl_p0_set3:
	v_readlane_b32 s22, v250, 26
	v_readlane_b32 s23, v250, 27
	v_readlane_b32 s24, v250, 36
	v_readlane_b32 s25, v250, 37
	v_mul_u32_u24_e32 v104, 0x10000, v102
	v_lshl_add_u32 v104, v103, 4, v104
	v_mul_u32_u24_e32 v105, 0x4000, v103
	v_lshl_add_u32 v105, v102, 4, v105
	s_add_u32 s24, s24, 0x4dc0000
	s_addc_u32 s25, s25, 0
	s_mov_b32 s48, 0x2000
	s_mov_b32 s49, 0x80000
	s_movk_i32 s50, 1
	s_mov_b32 s51, 6
	s_movk_i32 s52, 64
	s_movk_i32 s53, 0x1000
	s_mov_b32 s54, 0
	s_mov_b32 s55, 0
	s_movk_i32 s56, 0
	s_movk_i32 s47, 2048
	s_sub_i32 s4, s12, 1536
	s_and_b32 s4, s4, 2047
	s_branch .Lsl_p0_loop
.Lsl_p0_loop:
	s_cmp_ge_u32 s4, s47
	s_cbranch_scc1 .Lsl_p0_next
	s_add_i32 s16, s4, s56
	s_mul_i32 s17, s16, s50
	s_lshr_b32 s17, s17, s51
	s_mul_i32 s19, s17, s52
	s_sub_i32 s18, s16, s19
	s_mul_i32 s19, s17, s49
	s_lshl_b32 s20, s18, 7
	s_add_i32 s19, s19, s20
	v_add_u32_e32 v42, s19, v104
	s_cmp_eq_u32 s55, 0
	s_cbranch_scc1 .Lsl_p0_nks1
	s_lshl_b32 s19, s17, 8
	v_add_u32_e32 v43, s19, v110
	global_load_dwordx4 v[34:37], v43, s[44:45]
	global_load_dwordx4 v[38:41], v43, s[44:45] offset:16
.Lsl_p0_nks1:
	global_load_dwordx4 v[2:5], v42, s[22:23] nt
	v_add_u32_e32 v42, s48, v42
	global_load_dwordx4 v[6:9], v42, s[22:23] nt
	v_add_u32_e32 v42, s48, v42
	global_load_dwordx4 v[10:13], v42, s[22:23] nt
	v_add_u32_e32 v42, s48, v42
	global_load_dwordx4 v[14:17], v42, s[22:23] nt
	v_add_u32_e32 v42, s48, v42
	global_load_dwordx4 v[18:21], v42, s[22:23] nt
	v_add_u32_e32 v42, s48, v42
	global_load_dwordx4 v[22:25], v42, s[22:23] nt
	v_add_u32_e32 v42, s48, v42
	global_load_dwordx4 v[26:29], v42, s[22:23] nt
	v_add_u32_e32 v42, s48, v42
	global_load_dwordx4 v[30:33], v42, s[22:23] nt
	s_lshl_b32 s19, s18, 5
	s_cmp_eq_u32 s54, 0
	s_cbranch_scc1 .Lsl_p0_rmd2
	s_cmp_eq_u32 s54, 3
	s_cbranch_scc1 .Lsl_p0_rm33
	s_lshr_b32 s20, s19, 7
	s_lshl_b32 s20, s20, 8
	s_and_b32 s19, s19, 0x7f
	s_add_i32 s19, s19, s20
	s_and_b32 s20, s54, 2
	s_lshl_b32 s20, s20, 6
	s_add_i32 s19, s19, s20
	s_branch .Lsl_p0_rmd2

; __device__ __forceinline__ void tr_item(const float* __restrict__ W, int K, int N, bf16_t* WT, const float* __restrict__ kscale, int rowmode, int item, int lane) {
;     const int nblk = N >> 5, kb = item / nblk, nb = item - kb * nblk;
;     const int c = lane >> 3, q = lane & 7, k0 = kb * 64 + c * 8, n0 = nb * 32 + q * 4;
;     f32x4 v[8];
; #pragma unroll
;     for (int i = 0; i < 8; ++i) v[i] = __builtin_nontemporal_load((const f32x4*)(W + (size_t)(k0 + i) * N + n0));
;     if (kscale) { const f32x4 s0 = *(const f32x4*)(kscale + k0), s1 = *(const f32x4*)(kscale + k0 + 4);
; #pragma unroll
;         for (int i = 0; i < 4; ++i) { v[i] = v[i] * s0[i]; v[4 + i] = v[4 + i] * s1[i]; } }
;     int drow;
;     if (rowmode == 0) drow = n0;
;     else if (rowmode == 3) { const int g = n0 - pg8::C_GA; drow = g < 0 ? n0 : pg8::C_GA + (((g & 2047) >> 7) << 8) + ((g >> 11) << 7) + (g & 127); }
;     else drow = ((n0 >> 7) << 8) + (n0 & 127) + (rowmode == 2 ? 128 : 0);
.Lsl_p0_rmd2:
	s_mul_i32 s19, s19, s53
	s_lshl_b32 s20, s17, 7
	s_add_i32 s19, s19, s20
	v_add_u32_e32 v44, s19, v105
	s_add_i32 s4, s4, 2048
	s_cmp_ge_u32 s4, s47
	s_cbranch_scc1 .Lsl_p0_single
	s_add_i32 s16, s4, s56
	s_mul_i32 s17, s16, s50
	s_lshr_b32 s17, s17, s51
	s_mul_i32 s19, s17, s52
	s_sub_i32 s18, s16, s19
	s_mul_i32 s19, s17, s49
	s_lshl_b32 s20, s18, 7
	s_add_i32 s19, s19, s20
	v_add_u32_e32 v42, s19, v104
	s_cmp_eq_u32 s55, 0
	s_cbranch_scc1 .Lsl_p0_nks4
	s_lshl_b32 s19, s17, 8
	v_add_u32_e32 v43, s19, v110
	global_load_dwordx4 v[78:81], v43, s[44:45]
	global_load_dwordx4 v[82:85], v43, s[44:45] offset:16
.Lsl_p0_nks4:
	global_load_dwordx4 v[46:49], v42, s[22:23] nt
	v_add_u32_e32 v42, s48, v42
	global_load_dwordx4 v[50:53], v42, s[22:23] nt
	v_add_u32_e32 v42, s48, v42
	global_load_dwordx4 v[54:57], v42, s[22:23] nt
	v_add_u32_e32 v42, s48, v42
	global_load_dwordx4 v[58:61], v42, s[22:23] nt
	v_add_u32_e32 v42, s48, v42
	global_load_dwordx4 v[62:65], v42, s[22:23] nt
	v_add_u32_e32 v42, s48, v42
	global_load_dwordx4 v[66:69], v42, s[22:23] nt
	v_add_u32_e32 v42, s48, v42
	global_load_dwordx4 v[70:73], v42, s[22:23] nt
	v_add_u32_e32 v42, s48, v42
	global_load_dwordx4 v[74:77], v42, s[22:23] nt
	s_lshl_b32 s19, s18, 5
	s_cmp_eq_u32 s54, 0
	s_cbranch_scc1 .Lsl_p0_rmd5
	s_cmp_eq_u32 s54, 3
	s_cbranch_scc1 .Lsl_p0_rm36
	s_lshr_b32 s20, s19, 7
	s_lshl_b32 s20, s20, 8
	s_and_b32 s19, s19, 0x7f
	s_add_i32 s19, s19, s20
	s_and_b32 s20, s54, 2
	s_lshl_b32 s20, s20, 6
	s_add_i32 s19, s19, s20
	s_branch .Lsl_p0_rmd5

; __device__ __forceinline__ void tr_item(const float* __restrict__ W, int K, int N, bf16_t* WT, const float* __restrict__ kscale, int rowmode, int item, int lane) {
;     const int nblk = N >> 5, kb = item / nblk, nb = item - kb * nblk;
;     const int c = lane >> 3, q = lane & 7, k0 = kb * 64 + c * 8, n0 = nb * 32 + q * 4;
;     f32x4 v[8];
; #pragma unroll
;     for (int i = 0; i < 8; ++i) v[i] = __builtin_nontemporal_load((const f32x4*)(W + (size_t)(k0 + i) * N + n0));
;     if (kscale) { const f32x4 s0 = *(const f32x4*)(kscale + k0), s1 = *(const f32x4*)(kscale + k0 + 4);
; #pragma unroll
;         for (int i = 0; i < 4; ++i) { v[i] = v[i] * s0[i]; v[4 + i] = v[4 + i] * s1[i]; } }
;     int drow;
;     if (rowmode == 0) drow = n0;
;     else if (rowmode == 3) { const int g = n0 - pg8::C_GA; drow = g < 0 ? n0 : pg8::C_GA + (((g & 2047) >> 7) << 8) + ((g >> 11) << 7) + (g & 127); }
;     else drow = ((n0 >> 7) << 8) + (n0 & 127) + (rowmode == 2 ? 128 : 0);
.Lsl_p0_rmd5:
	s_mul_i32 s19, s19, s53
	s_lshl_b32 s20, s17, 7
	s_add_i32 s19, s19, s20
	v_add_u32_e32 v45, s19, v105
	s_add_i32 s4, s4, 2048
	s_cmp_ge_u32 s4, s47
	s_cbranch_scc1 .Lsl_p0_pair
	s_add_i32 s16, s4, s56
	s_mul_i32 s17, s16, s50
	s_lshr_b32 s17, s17, s51
	s_mul_i32 s19, s17, s52
	s_sub_i32 s18, s16, s19
	s_mul_i32 s19, s17, s49
	s_lshl_b32 s20, s18, 7
	s_add_i32 s19, s19, s20
	v_add_u32_e32 v42, s19, v104
	s_cmp_eq_u32 s55, 0
	s_cbranch_scc1 .Lsl_p0_nks7
	s_lshl_b32 s19, s17, 8
	v_add_u32_e32 v43, s19, v110
	global_load_dwordx4 v[144:147], v43, s[44:45]
	global_load_dwordx4 v[148:151], v43, s[44:45] offset:16
.Lsl_p0_nks7:
	global_load_dwordx4 v[112:115], v42, s[22:23] nt
	v_add_u32_e32 v42, s48, v42
	global_load_dwordx4 v[116:119], v42, s[22:23] nt
	v_add_u32_e32 v42, s48, v42
	global_load_dwordx4 v[120:123], v42, s[22:23] nt
	v_add_u32_e32 v42, s48, v42
	global_load_dwordx4 v[124:127], v42, s[22:23] nt
	v_add_u32_e32 v42, s48, v42
	global_load_dwordx4 v[128:131], v42, s[22:23] nt
	v_add_u32_e32 v42, s48, v42
	global_load_dwordx4 v[132:135], v42, s[22:23] nt
	v_add_u32_e32 v42, s48, v42
	global_load_dwordx4 v[136:139], v42, s[22:23] nt
	v_add_u32_e32 v42, s48, v42
	global_load_dwordx4 v[140:143], v42, s[22:23] nt
	s_lshl_b32 s19, s18, 5
	s_cmp_eq_u32 s54, 0
	s_cbranch_scc1 .Lsl_p0_rmd8
	s_cmp_eq_u32 s54, 3
	s_cbranch_scc1 .Lsl_p0_rm39
	s_lshr_b32 s20, s19, 7
	s_lshl_b32 s20, s20, 8
	s_and_b32 s19, s19, 0x7f
	s_add_i32 s19, s19, s20
	s_and_b32 s20, s54, 2
	s_lshl_b32 s20, s20, 6
	s_add_i32 s19, s19, s20
	s_branch .Lsl_p0_rmd8

; __device__ __forceinline__ unsigned cvt_pk_bf16(float lo, float hi) { unsigned r; asm volatile("v_cvt_pk_bf16_f32 %0, %1, %2" : "=v"(r) : "v"(lo), "v"(hi)); return r; }
; __device__ __forceinline__ void st16_wt(void* p, u32x4 v) { asm volatile("global_store_dwordx4 %0, %1, off sc1\n\ts_nop 1" :: "v"(p), "v"(v) : "memory"); }
; __device__ __forceinline__ void tr_item(const float* __restrict__ W, int K, int N, bf16_t* WT, const float* __restrict__ kscale, int rowmode, int item, int lane) {
;     ...
;     else drow = ((n0 >> 7) << 8) + (n0 & 127) + (rowmode == 2 ? 128 : 0);
; #pragma unroll
;     for (int e = 0; e < 4; ++e) { u32x4 o; o.x = cvt_pk_bf16(v[0][e], v[1][e]); o.y = cvt_pk_bf16(v[2][e], v[3][e]); o.z = cvt_pk_bf16(v[4][e], v[5][e]); o.w = cvt_pk_bf16(v[6][e], v[7][e]);
;         pg8::st16_wt(WT + (size_t)(drow + e) * K + k0, o); }
.Lsl_p0_rmd8:
	s_mul_i32 s19, s19, s53
	s_lshl_b32 s20, s17, 7
	s_add_i32 s19, s19, s20
	v_add_u32_e32 v111, s19, v105
	s_add_i32 s4, s4, 2048
	s_cmp_eq_u32 s55, 0
	s_cbranch_scc1 .Lsl_p0_w810
	s_waitcnt vmcnt(20)
	s_branch .Lsl_p0_wd11

; __device__ __forceinline__ unsigned cvt_pk_bf16(float lo, float hi) { unsigned r; asm volatile("v_cvt_pk_bf16_f32 %0, %1, %2" : "=v"(r) : "v"(lo), "v"(hi)); return r; }
; __device__ __forceinline__ void st16_wt(void* p, u32x4 v) { asm volatile("global_store_dwordx4 %0, %1, off sc1\n\ts_nop 1" :: "v"(p), "v"(v) : "memory"); }
; __device__ __forceinline__ void tr_item(const float* __restrict__ W, int K, int N, bf16_t* WT, const float* __restrict__ kscale, int rowmode, int item, int lane) {
;     ...
;     if (kscale) { const f32x4 s0 = *(const f32x4*)(kscale + k0), s1 = *(const f32x4*)(kscale + k0 + 4);
; #pragma unroll
;         for (int i = 0; i < 4; ++i) { v[i] = v[i] * s0[i]; v[4 + i] = v[4 + i] * s1[i]; } }
;     int drow;
;     if (rowmode == 0) drow = n0;
;     else if (rowmode == 3) { const int g = n0 - pg8::C_GA; drow = g < 0 ? n0 : pg8::C_GA + (((g & 2047) >> 7) << 8) + ((g >> 11) << 7) + (g & 127); }
;     else drow = ((n0 >> 7) << 8) + (n0 & 127) + (rowmode == 2 ? 128 : 0);
; #pragma unroll
;     for (int e = 0; e < 4; ++e) { u32x4 o; o.x = cvt_pk_bf16(v[0][e], v[1][e]); o.y = cvt_pk_bf16(v[2][e], v[3][e]); o.z = cvt_pk_bf16(v[4][e], v[5][e]); o.w = cvt_pk_bf16(v[6][e], v[7][e]);
;         pg8::st16_wt(WT + (size_t)(drow + e) * K + k0, o); }
.Lsl_p0_wd11:
	s_cmp_eq_u32 s55, 0
	s_cbranch_scc1 .Lsl_p0_nmul12
	v_mul_f32_e32 v2, v2, v34
	v_mul_f32_e32 v3, v3, v34
	v_mul_f32_e32 v4, v4, v34
	v_mul_f32_e32 v5, v5, v34
	v_mul_f32_e32 v6, v6, v35
	v_mul_f32_e32 v7, v7, v35
	v_mul_f32_e32 v8, v8, v35
	v_mul_f32_e32 v9, v9, v35
	v_mul_f32_e32 v10, v10, v36
	v_mul_f32_e32 v11, v11, v36
	v_mul_f32_e32 v12, v12, v36
	v_mul_f32_e32 v13, v13, v36
	v_mul_f32_e32 v14, v14, v37
	v_mul_f32_e32 v15, v15, v37
	v_mul_f32_e32 v16, v16, v37
	v_mul_f32_e32 v17, v17, v37
	v_mul_f32_e32 v18, v18, v38
	v_mul_f32_e32 v19, v19, v38
	v_mul_f32_e32 v20, v20, v38
	v_mul_f32_e32 v21, v21, v38
	v_mul_f32_e32 v22, v22, v39
	v_mul_f32_e32 v23, v23, v39
	v_mul_f32_e32 v24, v24, v39
	v_mul_f32_e32 v25, v25, v39
	v_mul_f32_e32 v26, v26, v40
	v_mul_f32_e32 v27, v27, v40
	v_mul_f32_e32 v28, v28, v40
	v_mul_f32_e32 v29, v29, v40
	v_mul_f32_e32 v30, v30, v41
	v_mul_f32_e32 v31, v31, v41
	v_mul_f32_e32 v32, v32, v41
	v_mul_f32_e32 v33, v33, v41
.Lsl_p0_nmul12:
	v_cvt_pk_bf16_f32 v86, v2, v6
	v_cvt_pk_bf16_f32 v87, v10, v14
	v_cvt_pk_bf16_f32 v88, v18, v22
	v_cvt_pk_bf16_f32 v89, v26, v30
	v_cvt_pk_bf16_f32 v90, v3, v7
	v_cvt_pk_bf16_f32 v91, v11, v15
	v_cvt_pk_bf16_f32 v92, v19, v23
	v_cvt_pk_bf16_f32 v93, v27, v31
	v_cvt_pk_bf16_f32 v94, v4, v8
	v_cvt_pk_bf16_f32 v95, v12, v16
	v_cvt_pk_bf16_f32 v96, v20, v24
	v_cvt_pk_bf16_f32 v97, v28, v32
	v_cvt_pk_bf16_f32 v98, v5, v9
	v_cvt_pk_bf16_f32 v99, v13, v17
	v_cvt_pk_bf16_f32 v100, v21, v25
	v_cvt_pk_bf16_f32 v101, v29, v33
	global_store_dwordx4 v44, v[86:89], s[24:25] sc1
	v_add_u32_e32 v44, s53, v44
	global_store_dwordx4 v44, v[90:93], s[24:25] sc1
	v_add_u32_e32 v44, s53, v44
	global_store_dwordx4 v44, v[94:97], s[24:25] sc1
	v_add_u32_e32 v44, s53, v44
	global_store_dwordx4 v44, v[98:101], s[24:25] sc1
	s_cmp_eq_u32 s55, 0
	s_cbranch_scc1 .Lsl_p0_w813
	s_waitcnt vmcnt(14)
	s_branch .Lsl_p0_wd14

; __device__ __forceinline__ unsigned cvt_pk_bf16(float lo, float hi) { unsigned r; asm volatile("v_cvt_pk_bf16_f32 %0, %1, %2" : "=v"(r) : "v"(lo), "v"(hi)); return r; }
; __device__ __forceinline__ void st16_wt(void* p, u32x4 v) { asm volatile("global_store_dwordx4 %0, %1, off sc1\n\ts_nop 1" :: "v"(p), "v"(v) : "memory"); }
; __device__ __forceinline__ void tr_item(const float* __restrict__ W, int K, int N, bf16_t* WT, const float* __restrict__ kscale, int rowmode, int item, int lane) {
;     ...
;     if (kscale) { const f32x4 s0 = *(const f32x4*)(kscale + k0), s1 = *(const f32x4*)(kscale + k0 + 4);
; #pragma unroll
;         for (int i = 0; i < 4; ++i) { v[i] = v[i] * s0[i]; v[4 + i] = v[4 + i] * s1[i]; } }
;     int drow;
;     if (rowmode == 0) drow = n0;
;     else if (rowmode == 3) { const int g = n0 - pg8::C_GA; drow = g < 0 ? n0 : pg8::C_GA + (((g & 2047) >> 7) << 8) + ((g >> 11) << 7) + (g & 127); }
;     else drow = ((n0 >> 7) << 8) + (n0 & 127) + (rowmode == 2 ? 128 : 0);
; #pragma unroll
;     for (int e = 0; e < 4; ++e) { u32x4 o; o.x = cvt_pk_bf16(v[0][e], v[1][e]); o.y = cvt_pk_bf16(v[2][e], v[3][e]); o.z = cvt_pk_bf16(v[4][e], v[5][e]); o.w = cvt_pk_bf16(v[6][e], v[7][e]);
;         pg8::st16_wt(WT + (size_t)(drow + e) * K + k0, o); }
.Lsl_p0_wd14:
	s_cmp_eq_u32 s55, 0
	s_cbranch_scc1 .Lsl_p0_nmul15
	v_mul_f32_e32 v46, v46, v78
	v_mul_f32_e32 v47, v47, v78
	v_mul_f32_e32 v48, v48, v78
	v_mul_f32_e32 v49, v49, v78
	v_mul_f32_e32 v50, v50, v79
	v_mul_f32_e32 v51, v51, v79
	v_mul_f32_e32 v52, v52, v79
	v_mul_f32_e32 v53, v53, v79
	v_mul_f32_e32 v54, v54, v80
	v_mul_f32_e32 v55, v55, v80
	v_mul_f32_e32 v56, v56, v80
	v_mul_f32_e32 v57, v57, v80
	v_mul_f32_e32 v58, v58, v81
	v_mul_f32_e32 v59, v59, v81
	v_mul_f32_e32 v60, v60, v81
	v_mul_f32_e32 v61, v61, v81
	v_mul_f32_e32 v62, v62, v82
	v_mul_f32_e32 v63, v63, v82
	v_mul_f32_e32 v64, v64, v82
	v_mul_f32_e32 v65, v65, v82
	v_mul_f32_e32 v66, v66, v83
	v_mul_f32_e32 v67, v67, v83
	v_mul_f32_e32 v68, v68, v83
	v_mul_f32_e32 v69, v69, v83
	v_mul_f32_e32 v70, v70, v84
	v_mul_f32_e32 v71, v71, v84
	v_mul_f32_e32 v72, v72, v84
	v_mul_f32_e32 v73, v73, v84
	v_mul_f32_e32 v74, v74, v85
	v_mul_f32_e32 v75, v75, v85
	v_mul_f32_e32 v76, v76, v85
	v_mul_f32_e32 v77, v77, v85
.Lsl_p0_nmul15:
	v_cvt_pk_bf16_f32 v86, v46, v50
	v_cvt_pk_bf16_f32 v87, v54, v58
	v_cvt_pk_bf16_f32 v88, v62, v66
	v_cvt_pk_bf16_f32 v89, v70, v74
	v_cvt_pk_bf16_f32 v90, v47, v51
	v_cvt_pk_bf16_f32 v91, v55, v59
	v_cvt_pk_bf16_f32 v92, v63, v67
	v_cvt_pk_bf16_f32 v93, v71, v75
	v_cvt_pk_bf16_f32 v94, v48, v52
	v_cvt_pk_bf16_f32 v95, v56, v60
	v_cvt_pk_bf16_f32 v96, v64, v68
	v_cvt_pk_bf16_f32 v97, v72, v76
	v_cvt_pk_bf16_f32 v98, v49, v53
	v_cvt_pk_bf16_f32 v99, v57, v61
	v_cvt_pk_bf16_f32 v100, v65, v69
	v_cvt_pk_bf16_f32 v101, v73, v77
	global_store_dwordx4 v45, v[86:89], s[24:25] sc1
	v_add_u32_e32 v45, s53, v45
	global_store_dwordx4 v45, v[90:93], s[24:25] sc1
	v_add_u32_e32 v45, s53, v45
	global_store_dwordx4 v45, v[94:97], s[24:25] sc1
	v_add_u32_e32 v45, s53, v45
	global_store_dwordx4 v45, v[98:101], s[24:25] sc1
	s_waitcnt vmcnt(8)
	s_cmp_eq_u32 s55, 0
	s_cbranch_scc1 .Lsl_p0_nmul16
	v_mul_f32_e32 v112, v112, v144
	v_mul_f32_e32 v113, v113, v144
	v_mul_f32_e32 v114, v114, v144
	v_mul_f32_e32 v115, v115, v144
	v_mul_f32_e32 v116, v116, v145
	v_mul_f32_e32 v117, v117, v145
	v_mul_f32_e32 v118, v118, v145
	v_mul_f32_e32 v119, v119, v145
	v_mul_f32_e32 v120, v120, v146
	v_mul_f32_e32 v121, v121, v146
	v_mul_f32_e32 v122, v122, v146
	v_mul_f32_e32 v123, v123, v146
	v_mul_f32_e32 v124, v124, v147
	v_mul_f32_e32 v125, v125, v147
	v_mul_f32_e32 v126, v126, v147
	v_mul_f32_e32 v127, v127, v147
	v_mul_f32_e32 v128, v128, v148
	v_mul_f32_e32 v129, v129, v148
	v_mul_f32_e32 v130, v130, v148
	v_mul_f32_e32 v131, v131, v148
	v_mul_f32_e32 v132, v132, v149
	v_mul_f32_e32 v133, v133, v149
	v_mul_f32_e32 v134, v134, v149
	v_mul_f32_e32 v135, v135, v149
	v_mul_f32_e32 v136, v136, v150
	v_mul_f32_e32 v137, v137, v150
	v_mul_f32_e32 v138, v138, v150
	v_mul_f32_e32 v139, v139, v150
	v_mul_f32_e32 v140, v140, v151
	v_mul_f32_e32 v141, v141, v151
	v_mul_f32_e32 v142, v142, v151
	v_mul_f32_e32 v143, v143, v151
.Lsl_p0_nmul16:
	v_cvt_pk_bf16_f32 v86, v112, v116
	v_cvt_pk_bf16_f32 v87, v120, v124
	v_cvt_pk_bf16_f32 v88, v128, v132
	v_cvt_pk_bf16_f32 v89, v136, v140
	v_cvt_pk_bf16_f32 v90, v113, v117
	v_cvt_pk_bf16_f32 v91, v121, v125
	v_cvt_pk_bf16_f32 v92, v129, v133
	v_cvt_pk_bf16_f32 v93, v137, v141
	v_cvt_pk_bf16_f32 v94, v114, v118
	v_cvt_pk_bf16_f32 v95, v122, v126
	v_cvt_pk_bf16_f32 v96, v130, v134
	v_cvt_pk_bf16_f32 v97, v138, v142
	v_cvt_pk_bf16_f32 v98, v115, v119
	v_cvt_pk_bf16_f32 v99, v123, v127
	v_cvt_pk_bf16_f32 v100, v131, v135
	v_cvt_pk_bf16_f32 v101, v139, v143
	global_store_dwordx4 v111, v[86:89], s[24:25] sc1
	v_add_u32_e32 v111, s53, v111
	global_store_dwordx4 v111, v[90:93], s[24:25] sc1
	v_add_u32_e32 v111, s53, v111
	global_store_dwordx4 v111, v[94:97], s[24:25] sc1
	v_add_u32_e32 v111, s53, v111
	global_store_dwordx4 v111, v[98:101], s[24:25] sc1
	s_branch .Lsl_p0_loop
.Lsl_p0_pair:
	s_cmp_eq_u32 s55, 0
	s_cbranch_scc1 .Lsl_p0_w817
	s_waitcnt vmcnt(10)
	s_branch .Lsl_p0_wd18

; __device__ __forceinline__ unsigned cvt_pk_bf16(float lo, float hi) { unsigned r; asm volatile("v_cvt_pk_bf16_f32 %0, %1, %2" : "=v"(r) : "v"(lo), "v"(hi)); return r; }
; __device__ __forceinline__ void st16_wt(void* p, u32x4 v) { asm volatile("global_store_dwordx4 %0, %1, off sc1\n\ts_nop 1" :: "v"(p), "v"(v) : "memory"); }
; __device__ __forceinline__ void tr_item(const float* __restrict__ W, int K, int N, bf16_t* WT, const float* __restrict__ kscale, int rowmode, int item, int lane) {
;     ...
;     if (kscale) { const f32x4 s0 = *(const f32x4*)(kscale + k0), s1 = *(const f32x4*)(kscale + k0 + 4);
; #pragma unroll
;         for (int i = 0; i < 4; ++i) { v[i] = v[i] * s0[i]; v[4 + i] = v[4 + i] * s1[i]; } }
;     int drow;
;     if (rowmode == 0) drow = n0;
;     else if (rowmode == 3) { const int g = n0 - pg8::C_GA; drow = g < 0 ? n0 : pg8::C_GA + (((g & 2047) >> 7) << 8) + ((g >> 11) << 7) + (g & 127); }
;     else drow = ((n0 >> 7) << 8) + (n0 & 127) + (rowmode == 2 ? 128 : 0);
; #pragma unroll
;     for (int e = 0; e < 4; ++e) { u32x4 o; o.x = cvt_pk_bf16(v[0][e], v[1][e]); o.y = cvt_pk_bf16(v[2][e], v[3][e]); o.z = cvt_pk_bf16(v[4][e], v[5][e]); o.w = cvt_pk_bf16(v[6][e], v[7][e]);
;         pg8::st16_wt(WT + (size_t)(drow + e) * K + k0, o); }
.Lsl_p0_nmul19:
	v_cvt_pk_bf16_f32 v86, v2, v6
	v_cvt_pk_bf16_f32 v87, v10, v14
	v_cvt_pk_bf16_f32 v88, v18, v22
	v_cvt_pk_bf16_f32 v89, v26, v30
	v_cvt_pk_bf16_f32 v90, v3, v7
	v_cvt_pk_bf16_f32 v91, v11, v15
	v_cvt_pk_bf16_f32 v92, v19, v23
	v_cvt_pk_bf16_f32 v93, v27, v31
	v_cvt_pk_bf16_f32 v94, v4, v8
	v_cvt_pk_bf16_f32 v95, v12, v16
	v_cvt_pk_bf16_f32 v96, v20, v24
	v_cvt_pk_bf16_f32 v97, v28, v32
	v_cvt_pk_bf16_f32 v98, v5, v9
	v_cvt_pk_bf16_f32 v99, v13, v17
	v_cvt_pk_bf16_f32 v100, v21, v25
	v_cvt_pk_bf16_f32 v101, v29, v33
	global_store_dwordx4 v44, v[86:89], s[24:25] sc1
	v_add_u32_e32 v44, s53, v44
	global_store_dwordx4 v44, v[90:93], s[24:25] sc1
	v_add_u32_e32 v44, s53, v44
	global_store_dwordx4 v44, v[94:97], s[24:25] sc1
	v_add_u32_e32 v44, s53, v44
	global_store_dwordx4 v44, v[98:101], s[24:25] sc1
	s_waitcnt vmcnt(4)
	s_cmp_eq_u32 s55, 0
	s_cbranch_scc1 .Lsl_p0_nmul20
	v_mul_f32_e32 v46, v46, v78
	v_mul_f32_e32 v47, v47, v78
	v_mul_f32_e32 v48, v48, v78
	v_mul_f32_e32 v49, v49, v78
	v_mul_f32_e32 v50, v50, v79
	v_mul_f32_e32 v51, v51, v79
	v_mul_f32_e32 v52, v52, v79
	v_mul_f32_e32 v53, v53, v79
	v_mul_f32_e32 v54, v54, v80
	v_mul_f32_e32 v55, v55, v80
	v_mul_f32_e32 v56, v56, v80
	v_mul_f32_e32 v57, v57, v80
	v_mul_f32_e32 v58, v58, v81
	v_mul_f32_e32 v59, v59, v81
	v_mul_f32_e32 v60, v60, v81
	v_mul_f32_e32 v61, v61, v81
	v_mul_f32_e32 v62, v62, v82
	v_mul_f32_e32 v63, v63, v82
	v_mul_f32_e32 v64, v64, v82
	v_mul_f32_e32 v65, v65, v82
	v_mul_f32_e32 v66, v66, v83
	v_mul_f32_e32 v67, v67, v83
	v_mul_f32_e32 v68, v68, v83
	v_mul_f32_e32 v69, v69, v83
	v_mul_f32_e32 v70, v70, v84
	v_mul_f32_e32 v71, v71, v84
	v_mul_f32_e32 v72, v72, v84
	v_mul_f32_e32 v73, v73, v84
	v_mul_f32_e32 v74, v74, v85
	v_mul_f32_e32 v75, v75, v85
	v_mul_f32_e32 v76, v76, v85
	v_mul_f32_e32 v77, v77, v85
.Lsl_p0_nmul20:
	v_cvt_pk_bf16_f32 v86, v46, v50
	v_cvt_pk_bf16_f32 v87, v54, v58
	v_cvt_pk_bf16_f32 v88, v62, v66
	v_cvt_pk_bf16_f32 v89, v70, v74
	v_cvt_pk_bf16_f32 v90, v47, v51
	v_cvt_pk_bf16_f32 v91, v55, v59
	v_cvt_pk_bf16_f32 v92, v63, v67
	v_cvt_pk_bf16_f32 v93, v71, v75
	v_cvt_pk_bf16_f32 v94, v48, v52
	v_cvt_pk_bf16_f32 v95, v56, v60
	v_cvt_pk_bf16_f32 v96, v64, v68
	v_cvt_pk_bf16_f32 v97, v72, v76
	v_cvt_pk_bf16_f32 v98, v49, v53
	v_cvt_pk_bf16_f32 v99, v57, v61
	v_cvt_pk_bf16_f32 v100, v65, v69
	v_cvt_pk_bf16_f32 v101, v73, v77
	global_store_dwordx4 v45, v[86:89], s[24:25] sc1
	v_add_u32_e32 v45, s53, v45
	global_store_dwordx4 v45, v[90:93], s[24:25] sc1
	v_add_u32_e32 v45, s53, v45
	global_store_dwordx4 v45, v[94:97], s[24:25] sc1
	v_add_u32_e32 v45, s53, v45
	global_store_dwordx4 v45, v[98:101], s[24:25] sc1
	s_branch .Lsl_p0_next
.Lsl_p0_single:
	s_waitcnt vmcnt(0)
	s_cmp_eq_u32 s55, 0
	s_cbranch_scc1 .Lsl_p0_nmul21
	v_mul_f32_e32 v2, v2, v34
	v_mul_f32_e32 v3, v3, v34
	v_mul_f32_e32 v4, v4, v34
	v_mul_f32_e32 v5, v5, v34
	v_mul_f32_e32 v6, v6, v35
	v_mul_f32_e32 v7, v7, v35
	v_mul_f32_e32 v8, v8, v35
	v_mul_f32_e32 v9, v9, v35
	v_mul_f32_e32 v10, v10, v36
	v_mul_f32_e32 v11, v11, v36
	v_mul_f32_e32 v12, v12, v36
	v_mul_f32_e32 v13, v13, v36
	v_mul_f32_e32 v14, v14, v37
	v_mul_f32_e32 v15, v15, v37
	v_mul_f32_e32 v16, v16, v37
	v_mul_f32_e32 v17, v17, v37
	v_mul_f32_e32 v18, v18, v38
	v_mul_f32_e32 v19, v19, v38
	v_mul_f32_e32 v20, v20, v38
	v_mul_f32_e32 v21, v21, v38
	v_mul_f32_e32 v22, v22, v39
	v_mul_f32_e32 v23, v23, v39
	v_mul_f32_e32 v24, v24, v39
	v_mul_f32_e32 v25, v25, v39
	v_mul_f32_e32 v26, v26, v40
	v_mul_f32_e32 v27, v27, v40
	v_mul_f32_e32 v28, v28, v40
	v_mul_f32_e32 v29, v29, v40
	v_mul_f32_e32 v30, v30, v41
	v_mul_f32_e32 v31, v31, v41
	v_mul_f32_e32 v32, v32, v41
	v_mul_f32_e32 v33, v33, v41
.Lsl_p0_nmul21:
	v_cvt_pk_bf16_f32 v86, v2, v6
	v_cvt_pk_bf16_f32 v87, v10, v14
	v_cvt_pk_bf16_f32 v88, v18, v22
	v_cvt_pk_bf16_f32 v89, v26, v30
	v_cvt_pk_bf16_f32 v90, v3, v7
	v_cvt_pk_bf16_f32 v91, v11, v15
	v_cvt_pk_bf16_f32 v92, v19, v23
	v_cvt_pk_bf16_f32 v93, v27, v31
	v_cvt_pk_bf16_f32 v94, v4, v8
	v_cvt_pk_bf16_f32 v95, v12, v16
	v_cvt_pk_bf16_f32 v96, v20, v24
	v_cvt_pk_bf16_f32 v97, v28, v32
	v_cvt_pk_bf16_f32 v98, v5, v9
	v_cvt_pk_bf16_f32 v99, v13, v17
	v_cvt_pk_bf16_f32 v100, v21, v25
	v_cvt_pk_bf16_f32 v101, v29, v33
	global_store_dwordx4 v44, v[86:89], s[24:25] sc1
	v_add_u32_e32 v44, s53, v44
	global_store_dwordx4 v44, v[90:93], s[24:25] sc1
	v_add_u32_e32 v44, s53, v44
	global_store_dwordx4 v44, v[94:97], s[24:25] sc1
	v_add_u32_e32 v44, s53, v44
	global_store_dwordx4 v44, v[98:101], s[24:25] sc1
.Lsl_p0_next:
	s_add_i32 s46, s46, 1
	s_branch .Lsl_p0_dispatch
.Lslot_p0_orig:
	s_mov_b32 s43, 0
	s_branch .LBB0_11
